# P9: next tile's SA11 stage issued before the epilogue stores; first K-iteration waits relaxed so it does not wait for store acks
# speedup vs baseline: 1.0074x; 1.0040x over previous
.LBB0_1224:
	v_readlane_b32 s27, v246, 0
	s_lshl_b32 s12, s12, 5
	s_add_i32 s25, s27, 0x18000
	s_and_b32 s24, s12, 0x60
	s_add_i32 s54, s25, s5
	s_mov_b64 s[12:13], 0x80
	s_lshl_b32 s17, s4, 13
	s_lshl_b32 s18, s24, 7
	v_lshl_add_u64 v[6:7], v[6:7], 0, s[12:13]
	s_mov_b32 m0, s54
	s_add_i32 s55, s54, 0x2000
	s_add_i32 s56, s48, 0x8000
	s_add_i32 s57, s48, 0xa000
	s_waitcnt vmcnt(4)
	s_barrier
	global_load_lds_dwordx4 v[6:7], off
	v_lshl_add_u64 v[4:5], v[4:5], 0, s[12:13]
	s_mov_b32 m0, s55
	s_add_u32 s14, s34, 0x40080
	global_load_lds_dwordx4 v[4:5], off
	v_lshl_add_u64 v[2:3], v[2:3], 0, s[12:13]
	s_mov_b32 m0, s56
	s_addc_u32 s15, s35, 0
	s_add_i32 s26, s27, 0x1c000
	global_load_lds_dwordx4 v[2:3], off
	v_lshl_add_u64 v[0:1], v[0:1], 0, s[12:13]
	s_mov_b32 m0, s57
	s_add_i32 s58, s26, s5
	global_load_lds_dwordx4 v[0:1], off
	v_lshl_add_u64 v[0:1], s[14:15], 0, v[128:129]
	s_mov_b32 m0, s58
	s_add_i32 s59, s58, 0x2000
	global_load_lds_dwordx4 v[0:1], off
	v_lshl_add_u64 v[0:1], s[14:15], 0, v[130:131]
	s_mov_b32 m0, s59
	v_bfe_u32 v2, v202, 4, 2
	global_load_lds_dwordx4 v[0:1], off
	v_lshlrev_b32_e32 v0, 4, v2
	v_lshlrev_b32_e32 v3, 2, v153
	v_lshl_or_b32 v1, v153, 6, v0
	v_and_b32_e32 v3, 32, v3
	v_or_b32_e32 v0, v0, v151
	v_bitop3_b32 v3, v1, s17, v3 bitop3:0xde
	v_bitop3_b32 v4, s18, v0, v155 bitop3:0xf6
	v_mul_u32_u24_e32 v0, 0x21000, v2
	v_and_b32_e32 v1, 63, v202
	v_lshl_or_b32 v160, s4, 6, v153
	v_cmp_eq_u32_e64 s[4:5], 0, v1
	v_lshlrev_b32_e32 v0, 2, v0
	v_mov_b32_e32 v1, v129
	v_lshl_add_u64 v[0:1], s[22:23], 0, v[0:1]
	s_mov_b64 s[18:19], 0x18db4000
	v_lshl_add_u64 v[132:133], v[0:1], 0, s[18:19]
	v_lshlrev_b32_e32 v0, 8, v202
	v_and_b32_e32 v0, 0xffff8000, v0
	v_lshlrev_b32_e32 v1, 11, v9
	v_or3_b32 v0, v147, v0, v1
	v_readlane_b32 s14, v246, 1
	v_add_u32_e32 v134, v0, v149
	v_lshlrev_b32_e32 v0, 4, v8
	s_ashr_i32 s61, s14, 31
	s_ashr_i32 s63, s74, 31
	v_and_b32_e32 v0, 0xffff8000, v0
	s_waitcnt vmcnt(6)
	v_readlane_b32 s15, v246, 2
	s_cmpk_gt_i32 s74, 0xef
	v_or3_b32 v0, v147, v0, v1
	s_mov_b32 s62, s14
	s_cselect_b64 s[14:15], -1, 0
	s_add_i32 s43, s74, 0xffffff10
	v_add_u32_e32 v136, v0, v149
	v_mbcnt_lo_u32_b32 v0, -1, 0
	s_mov_b32 s60, 0x21000
	s_mul_hi_u32 s64, s43, 9
	s_mul_i32 s65, s43, 9
	v_lshl_or_b32 v161, v2, 3, s24
	v_mov_b32_e32 v135, v129
	v_mov_b32_e32 v137, v129
	v_add_u32_e32 v162, s11, v4
	v_add_u32_e32 v163, s27, v3
	v_add_u32_e32 v164, s16, v4
	v_add_u32_e32 v165, s25, v4
	v_add_u32_e32 v166, s26, v4
	v_mbcnt_hi_u32_b32 v167, -1, v0
	s_mov_b32 s66, 0x42000
	s_mov_b32 s67, 0x63000
	s_waitcnt vmcnt(0)
	v_mov_b32_e32 v168, 0x358637bd
	v_readlane_b32 s92, v246, 0
	v_lshrrev_b32_e32 v203, 6, v202
	v_and_b32_e32 v247, 31, v202
	v_lshl_or_b32 v247, v203, 5, v247
	v_lshlrev_b32_e32 v247, 2, v247
	v_and_b32_e32 v203, 32, v202
	v_mul_u32_u24_e32 v203, 0x8400, v203
	v_add_u32_e32 v203, v203, v247
	s_add_i32 s92, s92, 0x20000
	s_nop 0
	v_add_u32_e32 v247, s92, v247
	s_movk_i32 s68, 0x1600
	v_mov_b64_e32 v[138:139], 0xac8
	v_mov_b64_e32 v[140:141], 0x57
	v_mov_b64_e32 v[142:143], 0xaff
	s_mov_b32 s11, 0
	s_barrier
	s_add_u32 s94, s30, 0x40080
	s_addc_u32 s95, s31, 0
	v_lshl_add_u64 v[144:145], s[94:95], 0, v[134:135]
	s_add_i32 m0, s48, 0xc000
	s_nop 0
	global_load_lds_dwordx4 v[144:145], off
	v_lshl_add_u64 v[144:145], s[94:95], 0, v[136:137]
	s_add_i32 m0, s48, 0xe000
	s_nop 0
	global_load_lds_dwordx4 v[144:145], off
	s_waitcnt vmcnt(0)
	s_branch .LBB0_1227

.LBB0_1242:
	s_xor_b64 s[26:27], s[36:37], -1
	s_and_b64 s[36:37], s[36:37], exec
	s_cselect_b32 s11, s19, s31
	s_cselect_b32 s17, s18, s30
	s_cselect_b32 s29, s25, s35
	s_cselect_b32 s38, s24, s34
	s_add_u32 s30, s30, 0x40080
	s_addc_u32 s31, s31, 0
	s_add_u32 s39, s34, 0x100
	s_addc_u32 s40, s35, 0
	s_mov_b32 s41, -2
	ds_read_b128 v[170:173], v162
	ds_read_b128 v[174:177], v162 offset:1024
	ds_read_b128 v[178:181], v162 offset:2048
	ds_read_b128 v[182:185], v162 offset:3072
	s_add_u32 s34, s30, 0xfffc0080
	s_addc_u32 s35, s31, -1
	s_cmp_eq_u32 s41, 12
	s_cselect_b32 s37, s11, s35
	s_cselect_b32 s36, s17, s34
	s_cselect_b32 s35, s29, s40
	s_cselect_b32 s34, s38, s39
	ds_read_b128 v[186:189], v163
	ds_read_b128 v[190:193], v163 offset:1024
	ds_read_b128 v[194:197], v163 offset:2048
	ds_read_b128 v[198:201], v163 offset:3072
	ds_read_b128 v[204:207], v163 offset:4096
	ds_read_b128 v[208:211], v163 offset:5120
	ds_read_b128 v[212:215], v163 offset:6144
	ds_read_b128 v[216:219], v163 offset:7168
	ds_read_b128 v[220:223], v164
	ds_read_b128 v[224:227], v164 offset:1024
	ds_read_b128 v[228:231], v164 offset:2048
	ds_read_b128 v[232:235], v164 offset:3072
	s_waitcnt lgkmcnt(0)
	s_waitcnt vmcnt(16)
	s_barrier
	s_setprio 1
	v_mfma_f32_16x16x32_bf16 v[124:127], v[170:173], v[186:189], 0
	v_mfma_f32_16x16x32_bf16 v[120:123], v[178:181], v[186:189], 0
	v_mfma_f32_16x16x32_bf16 v[112:115], v[170:173], v[194:197], 0
	v_mfma_f32_16x16x32_bf16 v[104:107], v[178:181], v[194:197], 0
	v_mfma_f32_16x16x32_bf16 v[96:99], v[170:173], v[204:207], 0
	v_mfma_f32_16x16x32_bf16 v[88:91], v[178:181], v[204:207], 0
	v_mfma_f32_16x16x32_bf16 v[80:83], v[170:173], v[212:215], 0
	v_mfma_f32_16x16x32_bf16 v[72:75], v[178:181], v[212:215], 0
	v_mfma_f32_16x16x32_bf16 v[124:127], v[174:177], v[190:193], v[124:127]
	v_mfma_f32_16x16x32_bf16 v[120:123], v[182:185], v[190:193], v[120:123]
	v_mfma_f32_16x16x32_bf16 v[112:115], v[174:177], v[198:201], v[112:115]
	v_mfma_f32_16x16x32_bf16 v[104:107], v[182:185], v[198:201], v[104:107]
	v_mfma_f32_16x16x32_bf16 v[96:99], v[174:177], v[208:211], v[96:99]
	v_mfma_f32_16x16x32_bf16 v[88:91], v[182:185], v[208:211], v[88:91]
	v_mfma_f32_16x16x32_bf16 v[80:83], v[174:177], v[216:219], v[80:83]
	v_mfma_f32_16x16x32_bf16 v[72:75], v[182:185], v[216:219], v[72:75]
	v_mfma_f32_16x16x32_bf16 v[116:119], v[220:223], v[186:189], 0
	v_mfma_f32_16x16x32_bf16 v[108:111], v[228:231], v[186:189], 0
	v_mfma_f32_16x16x32_bf16 v[100:103], v[220:223], v[194:197], 0
	v_mfma_f32_16x16x32_bf16 v[92:95], v[228:231], v[194:197], 0
	v_mfma_f32_16x16x32_bf16 v[84:87], v[220:223], v[204:207], 0
	v_mfma_f32_16x16x32_bf16 v[76:79], v[228:231], v[204:207], 0
	v_mfma_f32_16x16x32_bf16 v[68:71], v[220:223], v[212:215], 0
	v_mfma_f32_16x16x32_bf16 v[64:67], v[228:231], v[212:215], 0
	v_mfma_f32_16x16x32_bf16 v[116:119], v[224:227], v[190:193], v[116:119]
	v_mfma_f32_16x16x32_bf16 v[108:111], v[232:235], v[190:193], v[108:111]
	v_mfma_f32_16x16x32_bf16 v[100:103], v[224:227], v[198:201], v[100:103]
	v_mfma_f32_16x16x32_bf16 v[92:95], v[232:235], v[198:201], v[92:95]
	v_mfma_f32_16x16x32_bf16 v[84:87], v[224:227], v[208:211], v[84:87]
	v_mfma_f32_16x16x32_bf16 v[76:79], v[232:235], v[208:211], v[76:79]
	v_mfma_f32_16x16x32_bf16 v[68:71], v[224:227], v[216:219], v[68:71]
	v_mfma_f32_16x16x32_bf16 v[64:67], v[232:235], v[216:219], v[64:67]
	s_setprio 0
	s_barrier
	s_lshl_b32 s75, s42, 10
	s_add_u32 s76, s22, s75
	s_addc_u32 s77, s23, 0
	s_add_u32 s76, s76, 0x18db4000
	s_addc_u32 s77, s77, 0
	s_add_u32 s78, s76, 0x21000
	s_addc_u32 s79, s77, 0
	s_add_u32 s80, s78, 0x21000
	s_addc_u32 s81, s79, 0
	s_add_u32 s82, s80, 0x21000
	s_addc_u32 s83, s81, 0
	s_add_u32 s84, s82, 0x21000
	s_addc_u32 s85, s83, 0
	s_add_u32 s86, s84, 0x21000
	s_addc_u32 s87, s85, 0
	s_add_u32 s88, s86, 0x21000
	s_addc_u32 s89, s87, 0
	s_add_u32 s90, s88, 0x21000
	s_addc_u32 s91, s89, 0
	global_load_dword v242, v203, s[76:77]
	global_load_dword v243, v203, s[78:79]
	global_load_dword v250, v203, s[80:81]
	global_load_dword v251, v203, s[82:83]
	global_load_dword v252, v203, s[84:85]
	global_load_dword v253, v203, s[86:87]
	global_load_dword v254, v203, s[88:89]
	global_load_dword v255, v203, s[90:91]
	ds_read_b128 v[186:189], v163 offset:16384
	ds_read_b128 v[190:193], v163 offset:17408
	ds_read_b128 v[194:197], v163 offset:18432
	ds_read_b128 v[198:201], v163 offset:19456
	ds_read_b128 v[204:207], v163 offset:20480
	ds_read_b128 v[208:211], v163 offset:21504
	ds_read_b128 v[212:215], v163 offset:22528
	ds_read_b128 v[216:219], v163 offset:23552
	s_mov_b32 m0, s46
	v_lshl_add_u64 v[144:145], s[34:35], 0, v[128:129]
	global_load_lds_dwordx4 v[144:145], off
	v_lshl_add_u64 v[236:237], s[34:35], 0, v[130:131]
	s_mov_b32 m0, s47
	s_nop 0
	global_load_lds_dwordx4 v[236:237], off
	s_mov_b32 m0, s48
	v_lshl_add_u64 v[238:239], s[36:37], 0, v[128:129]
	global_load_lds_dwordx4 v[238:239], off
	v_lshl_add_u64 v[240:241], s[36:37], 0, v[130:131]
	s_mov_b32 m0, s49
	s_nop 0
	global_load_lds_dwordx4 v[240:241], off
	s_add_u32 s72, s34, 0x40000
	s_addc_u32 s73, s35, 0
	s_mov_b32 m0, s50
	v_lshl_add_u64 v[248:249], s[72:73], 0, v[128:129]
	global_load_lds_dwordx4 v[248:249], off
	v_lshl_add_u64 v[248:249], s[72:73], 0, v[130:131]
	s_mov_b32 m0, s51
	s_nop 0
	global_load_lds_dwordx4 v[248:249], off
	s_waitcnt lgkmcnt(0)
	s_waitcnt vmcnt(24)
	s_barrier
	s_setprio 1
	v_mfma_f32_16x16x32_bf16 v[60:63], v[170:173], v[186:189], 0
	v_mfma_f32_16x16x32_bf16 v[56:59], v[178:181], v[186:189], 0
	v_mfma_f32_16x16x32_bf16 v[48:51], v[170:173], v[194:197], 0
	v_mfma_f32_16x16x32_bf16 v[40:43], v[178:181], v[194:197], 0
	v_mfma_f32_16x16x32_bf16 v[32:35], v[170:173], v[204:207], 0
	v_mfma_f32_16x16x32_bf16 v[24:27], v[178:181], v[204:207], 0
	v_mfma_f32_16x16x32_bf16 v[16:19], v[170:173], v[212:215], 0
	v_mfma_f32_16x16x32_bf16 v[8:11], v[178:181], v[212:215], 0
	v_mfma_f32_16x16x32_bf16 v[60:63], v[174:177], v[190:193], v[60:63]
	v_mfma_f32_16x16x32_bf16 v[56:59], v[182:185], v[190:193], v[56:59]
	v_mfma_f32_16x16x32_bf16 v[48:51], v[174:177], v[198:201], v[48:51]
	v_mfma_f32_16x16x32_bf16 v[40:43], v[182:185], v[198:201], v[40:43]
	v_mfma_f32_16x16x32_bf16 v[32:35], v[174:177], v[208:211], v[32:35]
	v_mfma_f32_16x16x32_bf16 v[24:27], v[182:185], v[208:211], v[24:27]
	v_mfma_f32_16x16x32_bf16 v[16:19], v[174:177], v[216:219], v[16:19]
	v_mfma_f32_16x16x32_bf16 v[8:11], v[182:185], v[216:219], v[8:11]
	v_mfma_f32_16x16x32_bf16 v[52:55], v[220:223], v[186:189], 0
	v_mfma_f32_16x16x32_bf16 v[44:47], v[228:231], v[186:189], 0
	v_mfma_f32_16x16x32_bf16 v[36:39], v[220:223], v[194:197], 0
	v_mfma_f32_16x16x32_bf16 v[28:31], v[228:231], v[194:197], 0
	v_mfma_f32_16x16x32_bf16 v[20:23], v[220:223], v[204:207], 0
	v_mfma_f32_16x16x32_bf16 v[12:15], v[228:231], v[204:207], 0
	v_mfma_f32_16x16x32_bf16 v[4:7], v[220:223], v[212:215], 0
	v_mfma_f32_16x16x32_bf16 v[0:3], v[228:231], v[212:215], 0
	v_mfma_f32_16x16x32_bf16 v[52:55], v[224:227], v[190:193], v[52:55]
	v_mfma_f32_16x16x32_bf16 v[44:47], v[232:235], v[190:193], v[44:47]
	v_mfma_f32_16x16x32_bf16 v[36:39], v[224:227], v[198:201], v[36:39]
	v_mfma_f32_16x16x32_bf16 v[28:31], v[232:235], v[198:201], v[28:31]
	v_mfma_f32_16x16x32_bf16 v[20:23], v[224:227], v[208:211], v[20:23]
	v_mfma_f32_16x16x32_bf16 v[12:15], v[232:235], v[208:211], v[12:15]
	v_mfma_f32_16x16x32_bf16 v[4:7], v[224:227], v[216:219], v[4:7]
	v_mfma_f32_16x16x32_bf16 v[0:3], v[232:235], v[216:219], v[0:3]
	s_setprio 0
	s_barrier
	ds_read_b128 v[170:173], v165
	ds_read_b128 v[174:177], v165 offset:1024
	ds_read_b128 v[178:181], v165 offset:2048
	ds_read_b128 v[182:185], v165 offset:3072
	s_add_u32 s36, s36, 0x40000
	s_addc_u32 s37, s37, 0
	s_mov_b32 m0, s52
	v_lshl_add_u64 v[220:221], s[36:37], 0, v[128:129]
	ds_read_b128 v[186:189], v163 offset:32768
	ds_read_b128 v[190:193], v163 offset:33792
	ds_read_b128 v[194:197], v163 offset:34816
	ds_read_b128 v[198:201], v163 offset:35840
	ds_read_b128 v[204:207], v163 offset:36864
	ds_read_b128 v[208:211], v163 offset:37888
	ds_read_b128 v[212:215], v163 offset:38912
	ds_read_b128 v[216:219], v163 offset:39936
	global_load_lds_dwordx4 v[220:221], off
	v_lshl_add_u64 v[220:221], s[36:37], 0, v[130:131]
	s_mov_b32 m0, s53
	s_nop 0
	global_load_lds_dwordx4 v[220:221], off
	ds_read_b128 v[220:223], v166
	ds_read_b128 v[224:227], v166 offset:1024
	ds_read_b128 v[228:231], v166 offset:2048
	ds_read_b128 v[232:235], v166 offset:3072
	s_waitcnt lgkmcnt(0)
	s_waitcnt vmcnt(24)
	s_barrier
	s_setprio 1
	v_mfma_f32_16x16x32_bf16 v[124:127], v[170:173], v[186:189], v[124:127]
	v_mfma_f32_16x16x32_bf16 v[120:123], v[178:181], v[186:189], v[120:123]
	v_mfma_f32_16x16x32_bf16 v[112:115], v[170:173], v[194:197], v[112:115]
	v_mfma_f32_16x16x32_bf16 v[104:107], v[178:181], v[194:197], v[104:107]
	v_mfma_f32_16x16x32_bf16 v[96:99], v[170:173], v[204:207], v[96:99]
	v_mfma_f32_16x16x32_bf16 v[88:91], v[178:181], v[204:207], v[88:91]
	v_mfma_f32_16x16x32_bf16 v[80:83], v[170:173], v[212:215], v[80:83]
	v_mfma_f32_16x16x32_bf16 v[72:75], v[178:181], v[212:215], v[72:75]
	v_mfma_f32_16x16x32_bf16 v[124:127], v[174:177], v[190:193], v[124:127]
	v_mfma_f32_16x16x32_bf16 v[120:123], v[182:185], v[190:193], v[120:123]
	v_mfma_f32_16x16x32_bf16 v[112:115], v[174:177], v[198:201], v[112:115]
	v_mfma_f32_16x16x32_bf16 v[104:107], v[182:185], v[198:201], v[104:107]
	v_mfma_f32_16x16x32_bf16 v[96:99], v[174:177], v[208:211], v[96:99]
	v_mfma_f32_16x16x32_bf16 v[88:91], v[182:185], v[208:211], v[88:91]
	v_mfma_f32_16x16x32_bf16 v[80:83], v[174:177], v[216:219], v[80:83]
	v_mfma_f32_16x16x32_bf16 v[72:75], v[182:185], v[216:219], v[72:75]
	v_mfma_f32_16x16x32_bf16 v[116:119], v[220:223], v[186:189], v[116:119]
	v_mfma_f32_16x16x32_bf16 v[108:111], v[228:231], v[186:189], v[108:111]
	v_mfma_f32_16x16x32_bf16 v[100:103], v[220:223], v[194:197], v[100:103]
	v_mfma_f32_16x16x32_bf16 v[92:95], v[228:231], v[194:197], v[92:95]
	v_mfma_f32_16x16x32_bf16 v[84:87], v[220:223], v[204:207], v[84:87]
	v_mfma_f32_16x16x32_bf16 v[76:79], v[228:231], v[204:207], v[76:79]
	v_mfma_f32_16x16x32_bf16 v[68:71], v[220:223], v[212:215], v[68:71]
	v_mfma_f32_16x16x32_bf16 v[64:67], v[228:231], v[212:215], v[64:67]
	v_mfma_f32_16x16x32_bf16 v[116:119], v[224:227], v[190:193], v[116:119]
	v_mfma_f32_16x16x32_bf16 v[108:111], v[232:235], v[190:193], v[108:111]
	v_mfma_f32_16x16x32_bf16 v[100:103], v[224:227], v[198:201], v[100:103]
	v_mfma_f32_16x16x32_bf16 v[92:95], v[232:235], v[198:201], v[92:95]
	v_mfma_f32_16x16x32_bf16 v[84:87], v[224:227], v[208:211], v[84:87]
	v_mfma_f32_16x16x32_bf16 v[76:79], v[232:235], v[208:211], v[76:79]
	v_mfma_f32_16x16x32_bf16 v[68:71], v[224:227], v[216:219], v[68:71]
	v_mfma_f32_16x16x32_bf16 v[64:67], v[232:235], v[216:219], v[64:67]
	s_setprio 0
	s_barrier
	ds_read_b128 v[186:189], v163 offset:49152
	ds_read_b128 v[190:193], v163 offset:50176
	ds_read_b128 v[194:197], v163 offset:51200
	ds_read_b128 v[198:201], v163 offset:52224
	ds_read_b128 v[204:207], v163 offset:53248
	ds_read_b128 v[208:211], v163 offset:54272
	ds_read_b128 v[212:215], v163 offset:55296
	ds_read_b128 v[216:219], v163 offset:56320
	s_mov_b32 m0, s54
	v_lshl_add_u64 v[144:145], v[144:145], 0, s[12:13]
	global_load_lds_dwordx4 v[144:145], off
	v_lshl_add_u64 v[144:145], v[236:237], 0, s[12:13]
	s_mov_b32 m0, s55
	s_nop 0
	global_load_lds_dwordx4 v[144:145], off
	s_mov_b32 m0, s56
	v_lshl_add_u64 v[144:145], v[238:239], 0, s[12:13]
	global_load_lds_dwordx4 v[144:145], off
	v_lshl_add_u64 v[144:145], v[240:241], 0, s[12:13]
	s_mov_b32 m0, s57
	s_nop 0
	global_load_lds_dwordx4 v[144:145], off
	s_add_u32 s34, s34, 0x40080
	s_addc_u32 s35, s35, 0
	s_mov_b32 m0, s58
	v_lshl_add_u64 v[144:145], s[34:35], 0, v[128:129]
	global_load_lds_dwordx4 v[144:145], off
	v_lshl_add_u64 v[144:145], s[34:35], 0, v[130:131]
	s_mov_b32 m0, s59
	s_nop 0
	global_load_lds_dwordx4 v[144:145], off
	s_waitcnt lgkmcnt(0)
	s_waitcnt vmcnt(8)
	s_barrier
	s_setprio 1
	v_mfma_f32_16x16x32_bf16 v[60:63], v[170:173], v[186:189], v[60:63]
	v_mfma_f32_16x16x32_bf16 v[56:59], v[178:181], v[186:189], v[56:59]
	v_add_f32_e32 v242, v242, v243
	v_mfma_f32_16x16x32_bf16 v[48:51], v[170:173], v[194:197], v[48:51]
	v_add_f32_e32 v250, v250, v251
	v_mfma_f32_16x16x32_bf16 v[40:43], v[178:181], v[194:197], v[40:43]
	v_add_f32_e32 v252, v252, v253
	v_mfma_f32_16x16x32_bf16 v[32:35], v[170:173], v[204:207], v[32:35]
	v_add_f32_e32 v254, v254, v255
	v_mfma_f32_16x16x32_bf16 v[24:27], v[178:181], v[204:207], v[24:27]
	v_add_f32_e32 v242, v242, v250
	v_mfma_f32_16x16x32_bf16 v[16:19], v[170:173], v[212:215], v[16:19]
	v_add_f32_e32 v252, v252, v254
	v_mfma_f32_16x16x32_bf16 v[8:11], v[178:181], v[212:215], v[8:11]
	v_add_f32_e32 v242, v242, v252
	v_mfma_f32_16x16x32_bf16 v[60:63], v[174:177], v[190:193], v[60:63]
	v_mov_b32_e32 v243, v242
	v_mfma_f32_16x16x32_bf16 v[56:59], v[182:185], v[190:193], v[56:59]
	v_mfma_f32_16x16x32_bf16 v[48:51], v[174:177], v[198:201], v[48:51]
	s_nop 1
	v_permlane32_swap_b32_e32 v242, v243
	v_mfma_f32_16x16x32_bf16 v[40:43], v[182:185], v[198:201], v[40:43]
	v_mfma_f32_16x16x32_bf16 v[32:35], v[174:177], v[208:211], v[32:35]
	v_add_f32_e32 v242, v242, v243
	v_mfma_f32_16x16x32_bf16 v[24:27], v[182:185], v[208:211], v[24:27]
	v_fmamk_f32 v242, v242, 0x3a800000, v168
	v_mfma_f32_16x16x32_bf16 v[16:19], v[174:177], v[216:219], v[16:19]
	v_rsq_f32_e32 v242, v242
	v_mfma_f32_16x16x32_bf16 v[8:11], v[182:185], v[216:219], v[8:11]
	v_mfma_f32_16x16x32_bf16 v[52:55], v[220:223], v[186:189], v[52:55]
	s_nop 0
	ds_write_b32 v247, v242
	v_mfma_f32_16x16x32_bf16 v[44:47], v[228:231], v[186:189], v[44:47]
	v_mfma_f32_16x16x32_bf16 v[36:39], v[220:223], v[194:197], v[36:39]
	v_mfma_f32_16x16x32_bf16 v[28:31], v[228:231], v[194:197], v[28:31]
	v_mfma_f32_16x16x32_bf16 v[20:23], v[220:223], v[204:207], v[20:23]
	v_mfma_f32_16x16x32_bf16 v[12:15], v[228:231], v[204:207], v[12:15]
	v_mfma_f32_16x16x32_bf16 v[4:7], v[220:223], v[212:215], v[4:7]
	v_mfma_f32_16x16x32_bf16 v[0:3], v[228:231], v[212:215], v[0:3]
	v_mfma_f32_16x16x32_bf16 v[52:55], v[224:227], v[190:193], v[52:55]
	v_mfma_f32_16x16x32_bf16 v[44:47], v[232:235], v[190:193], v[44:47]
	v_mfma_f32_16x16x32_bf16 v[36:39], v[224:227], v[198:201], v[36:39]
	v_mfma_f32_16x16x32_bf16 v[28:31], v[232:235], v[198:201], v[28:31]
	v_mfma_f32_16x16x32_bf16 v[20:23], v[224:227], v[208:211], v[20:23]
	v_mfma_f32_16x16x32_bf16 v[12:15], v[232:235], v[208:211], v[12:15]
	v_mfma_f32_16x16x32_bf16 v[4:7], v[224:227], v[216:219], v[4:7]
	v_mfma_f32_16x16x32_bf16 v[0:3], v[232:235], v[216:219], v[0:3]
	s_setprio 0
	s_add_i32 s41, s41, 2
	s_add_u32 s30, s30, 0x100
	s_addc_u32 s31, s31, 0
	s_add_u32 s39, s39, 0x100
	s_addc_u32 s40, s40, 0
	s_cmp_gt_u32 s41, 13
	s_barrier
.LBB0_1243:
	ds_read_b128 v[170:173], v162
	ds_read_b128 v[174:177], v162 offset:1024
	ds_read_b128 v[178:181], v162 offset:2048
	ds_read_b128 v[182:185], v162 offset:3072
	s_add_u32 s34, s30, 0xfffc0080
	s_addc_u32 s35, s31, -1
	s_cmp_eq_u32 s41, 12
	s_cselect_b32 s37, s11, s35
	s_cselect_b32 s36, s17, s34
	s_cselect_b32 s35, s29, s40
	s_cselect_b32 s34, s38, s39
	v_lshl_add_u64 v[144:145], s[30:31], 0, v[134:135]
	s_add_i32 m0, s48, 0xc000
	ds_read_b128 v[186:189], v163
	ds_read_b128 v[190:193], v163 offset:1024
	ds_read_b128 v[194:197], v163 offset:2048
	ds_read_b128 v[198:201], v163 offset:3072
	ds_read_b128 v[204:207], v163 offset:4096
	ds_read_b128 v[208:211], v163 offset:5120
	ds_read_b128 v[212:215], v163 offset:6144
	ds_read_b128 v[216:219], v163 offset:7168
	global_load_lds_dwordx4 v[144:145], off
	v_lshl_add_u64 v[144:145], s[30:31], 0, v[136:137]
	s_add_i32 m0, s48, 0xe000
	s_nop 0
	global_load_lds_dwordx4 v[144:145], off
	ds_read_b128 v[220:223], v164
	ds_read_b128 v[224:227], v164 offset:1024
	ds_read_b128 v[228:231], v164 offset:2048
	ds_read_b128 v[232:235], v164 offset:3072
	s_waitcnt lgkmcnt(0)
	s_waitcnt vmcnt(8)
	s_barrier
	s_setprio 1
	v_mfma_f32_16x16x32_bf16 v[124:127], v[170:173], v[186:189], v[124:127]
	v_mfma_f32_16x16x32_bf16 v[120:123], v[178:181], v[186:189], v[120:123]
	v_mfma_f32_16x16x32_bf16 v[112:115], v[170:173], v[194:197], v[112:115]
	v_mfma_f32_16x16x32_bf16 v[104:107], v[178:181], v[194:197], v[104:107]
	v_mfma_f32_16x16x32_bf16 v[96:99], v[170:173], v[204:207], v[96:99]
	v_mfma_f32_16x16x32_bf16 v[88:91], v[178:181], v[204:207], v[88:91]
	v_mfma_f32_16x16x32_bf16 v[80:83], v[170:173], v[212:215], v[80:83]
	v_mfma_f32_16x16x32_bf16 v[72:75], v[178:181], v[212:215], v[72:75]
	v_mfma_f32_16x16x32_bf16 v[124:127], v[174:177], v[190:193], v[124:127]
	v_mfma_f32_16x16x32_bf16 v[120:123], v[182:185], v[190:193], v[120:123]
	v_mfma_f32_16x16x32_bf16 v[112:115], v[174:177], v[198:201], v[112:115]
	v_mfma_f32_16x16x32_bf16 v[104:107], v[182:185], v[198:201], v[104:107]
	v_mfma_f32_16x16x32_bf16 v[96:99], v[174:177], v[208:211], v[96:99]
	v_mfma_f32_16x16x32_bf16 v[88:91], v[182:185], v[208:211], v[88:91]
	v_mfma_f32_16x16x32_bf16 v[80:83], v[174:177], v[216:219], v[80:83]
	v_mfma_f32_16x16x32_bf16 v[72:75], v[182:185], v[216:219], v[72:75]
	v_mfma_f32_16x16x32_bf16 v[116:119], v[220:223], v[186:189], v[116:119]
	v_mfma_f32_16x16x32_bf16 v[108:111], v[228:231], v[186:189], v[108:111]
	v_mfma_f32_16x16x32_bf16 v[100:103], v[220:223], v[194:197], v[100:103]
	v_mfma_f32_16x16x32_bf16 v[92:95], v[228:231], v[194:197], v[92:95]
	v_mfma_f32_16x16x32_bf16 v[84:87], v[220:223], v[204:207], v[84:87]
	v_mfma_f32_16x16x32_bf16 v[76:79], v[228:231], v[204:207], v[76:79]
	v_mfma_f32_16x16x32_bf16 v[68:71], v[220:223], v[212:215], v[68:71]
	v_mfma_f32_16x16x32_bf16 v[64:67], v[228:231], v[212:215], v[64:67]
	v_mfma_f32_16x16x32_bf16 v[116:119], v[224:227], v[190:193], v[116:119]
	v_mfma_f32_16x16x32_bf16 v[108:111], v[232:235], v[190:193], v[108:111]
	v_mfma_f32_16x16x32_bf16 v[100:103], v[224:227], v[198:201], v[100:103]
	v_mfma_f32_16x16x32_bf16 v[92:95], v[232:235], v[198:201], v[92:95]
	v_mfma_f32_16x16x32_bf16 v[84:87], v[224:227], v[208:211], v[84:87]
	v_mfma_f32_16x16x32_bf16 v[76:79], v[232:235], v[208:211], v[76:79]
	v_mfma_f32_16x16x32_bf16 v[68:71], v[224:227], v[216:219], v[68:71]
	v_mfma_f32_16x16x32_bf16 v[64:67], v[232:235], v[216:219], v[64:67]
	s_setprio 0
	s_barrier
	ds_read_b128 v[186:189], v163 offset:16384
	ds_read_b128 v[190:193], v163 offset:17408
	ds_read_b128 v[194:197], v163 offset:18432
	ds_read_b128 v[198:201], v163 offset:19456
	ds_read_b128 v[204:207], v163 offset:20480
	ds_read_b128 v[208:211], v163 offset:21504
	ds_read_b128 v[212:215], v163 offset:22528
	ds_read_b128 v[216:219], v163 offset:23552
	s_mov_b32 m0, s46
	v_lshl_add_u64 v[144:145], s[34:35], 0, v[128:129]
	global_load_lds_dwordx4 v[144:145], off
	v_lshl_add_u64 v[236:237], s[34:35], 0, v[130:131]
	s_mov_b32 m0, s47
	s_nop 0
	global_load_lds_dwordx4 v[236:237], off
	s_mov_b32 m0, s48
	v_lshl_add_u64 v[238:239], s[36:37], 0, v[128:129]
	global_load_lds_dwordx4 v[238:239], off
	v_lshl_add_u64 v[240:241], s[36:37], 0, v[130:131]
	s_mov_b32 m0, s49
	s_nop 0
	global_load_lds_dwordx4 v[240:241], off
	s_add_u32 s72, s34, 0x40000
	s_addc_u32 s73, s35, 0
	s_mov_b32 m0, s50
	v_lshl_add_u64 v[248:249], s[72:73], 0, v[128:129]
	global_load_lds_dwordx4 v[248:249], off
	v_lshl_add_u64 v[248:249], s[72:73], 0, v[130:131]
	s_mov_b32 m0, s51
	s_nop 0
	global_load_lds_dwordx4 v[248:249], off
	s_waitcnt lgkmcnt(0)
	s_waitcnt vmcnt(8)
	s_barrier
	s_setprio 1
	v_mfma_f32_16x16x32_bf16 v[60:63], v[170:173], v[186:189], v[60:63]
	v_mfma_f32_16x16x32_bf16 v[56:59], v[178:181], v[186:189], v[56:59]
	v_mfma_f32_16x16x32_bf16 v[48:51], v[170:173], v[194:197], v[48:51]
	v_mfma_f32_16x16x32_bf16 v[40:43], v[178:181], v[194:197], v[40:43]
	v_mfma_f32_16x16x32_bf16 v[32:35], v[170:173], v[204:207], v[32:35]
	v_mfma_f32_16x16x32_bf16 v[24:27], v[178:181], v[204:207], v[24:27]
	v_mfma_f32_16x16x32_bf16 v[16:19], v[170:173], v[212:215], v[16:19]
	v_mfma_f32_16x16x32_bf16 v[8:11], v[178:181], v[212:215], v[8:11]
	v_mfma_f32_16x16x32_bf16 v[60:63], v[174:177], v[190:193], v[60:63]
	v_mfma_f32_16x16x32_bf16 v[56:59], v[182:185], v[190:193], v[56:59]
	v_mfma_f32_16x16x32_bf16 v[48:51], v[174:177], v[198:201], v[48:51]
	v_mfma_f32_16x16x32_bf16 v[40:43], v[182:185], v[198:201], v[40:43]
	v_mfma_f32_16x16x32_bf16 v[32:35], v[174:177], v[208:211], v[32:35]
	v_mfma_f32_16x16x32_bf16 v[24:27], v[182:185], v[208:211], v[24:27]
	v_mfma_f32_16x16x32_bf16 v[16:19], v[174:177], v[216:219], v[16:19]
	v_mfma_f32_16x16x32_bf16 v[8:11], v[182:185], v[216:219], v[8:11]
	v_mfma_f32_16x16x32_bf16 v[52:55], v[220:223], v[186:189], v[52:55]
	v_mfma_f32_16x16x32_bf16 v[44:47], v[228:231], v[186:189], v[44:47]
	v_mfma_f32_16x16x32_bf16 v[36:39], v[220:223], v[194:197], v[36:39]
	v_mfma_f32_16x16x32_bf16 v[28:31], v[228:231], v[194:197], v[28:31]
	v_mfma_f32_16x16x32_bf16 v[20:23], v[220:223], v[204:207], v[20:23]
	v_mfma_f32_16x16x32_bf16 v[12:15], v[228:231], v[204:207], v[12:15]
	v_mfma_f32_16x16x32_bf16 v[4:7], v[220:223], v[212:215], v[4:7]
	v_mfma_f32_16x16x32_bf16 v[0:3], v[228:231], v[212:215], v[0:3]
	v_mfma_f32_16x16x32_bf16 v[52:55], v[224:227], v[190:193], v[52:55]
	v_mfma_f32_16x16x32_bf16 v[44:47], v[232:235], v[190:193], v[44:47]
	v_mfma_f32_16x16x32_bf16 v[36:39], v[224:227], v[198:201], v[36:39]
	v_mfma_f32_16x16x32_bf16 v[28:31], v[232:235], v[198:201], v[28:31]
	v_mfma_f32_16x16x32_bf16 v[20:23], v[224:227], v[208:211], v[20:23]
	v_mfma_f32_16x16x32_bf16 v[12:15], v[232:235], v[208:211], v[12:15]
	v_mfma_f32_16x16x32_bf16 v[4:7], v[224:227], v[216:219], v[4:7]
	v_mfma_f32_16x16x32_bf16 v[0:3], v[232:235], v[216:219], v[0:3]
	s_setprio 0
	s_barrier
	ds_read_b128 v[170:173], v165
	ds_read_b128 v[174:177], v165 offset:1024
	ds_read_b128 v[178:181], v165 offset:2048
	ds_read_b128 v[182:185], v165 offset:3072
	s_add_u32 s36, s36, 0x40000
	s_addc_u32 s37, s37, 0
	s_mov_b32 m0, s52
	v_lshl_add_u64 v[220:221], s[36:37], 0, v[128:129]
	ds_read_b128 v[186:189], v163 offset:32768
	ds_read_b128 v[190:193], v163 offset:33792
	ds_read_b128 v[194:197], v163 offset:34816
	ds_read_b128 v[198:201], v163 offset:35840
	ds_read_b128 v[204:207], v163 offset:36864
	ds_read_b128 v[208:211], v163 offset:37888
	ds_read_b128 v[212:215], v163 offset:38912
	ds_read_b128 v[216:219], v163 offset:39936
	global_load_lds_dwordx4 v[220:221], off
	v_lshl_add_u64 v[220:221], s[36:37], 0, v[130:131]
	s_mov_b32 m0, s53
	s_nop 0
	global_load_lds_dwordx4 v[220:221], off
	ds_read_b128 v[220:223], v166
	ds_read_b128 v[224:227], v166 offset:1024
	ds_read_b128 v[228:231], v166 offset:2048
	ds_read_b128 v[232:235], v166 offset:3072
	s_waitcnt lgkmcnt(0)
	s_waitcnt vmcnt(8)
	s_barrier
	s_setprio 1
	v_mfma_f32_16x16x32_bf16 v[124:127], v[170:173], v[186:189], v[124:127]
	v_mfma_f32_16x16x32_bf16 v[120:123], v[178:181], v[186:189], v[120:123]
	v_mfma_f32_16x16x32_bf16 v[112:115], v[170:173], v[194:197], v[112:115]
	v_mfma_f32_16x16x32_bf16 v[104:107], v[178:181], v[194:197], v[104:107]
	v_mfma_f32_16x16x32_bf16 v[96:99], v[170:173], v[204:207], v[96:99]
	v_mfma_f32_16x16x32_bf16 v[88:91], v[178:181], v[204:207], v[88:91]
	v_mfma_f32_16x16x32_bf16 v[80:83], v[170:173], v[212:215], v[80:83]
	v_mfma_f32_16x16x32_bf16 v[72:75], v[178:181], v[212:215], v[72:75]
	v_mfma_f32_16x16x32_bf16 v[124:127], v[174:177], v[190:193], v[124:127]
	v_mfma_f32_16x16x32_bf16 v[120:123], v[182:185], v[190:193], v[120:123]
	v_mfma_f32_16x16x32_bf16 v[112:115], v[174:177], v[198:201], v[112:115]
	v_mfma_f32_16x16x32_bf16 v[104:107], v[182:185], v[198:201], v[104:107]
	v_mfma_f32_16x16x32_bf16 v[96:99], v[174:177], v[208:211], v[96:99]
	v_mfma_f32_16x16x32_bf16 v[88:91], v[182:185], v[208:211], v[88:91]
	v_mfma_f32_16x16x32_bf16 v[80:83], v[174:177], v[216:219], v[80:83]
	v_mfma_f32_16x16x32_bf16 v[72:75], v[182:185], v[216:219], v[72:75]
	v_mfma_f32_16x16x32_bf16 v[116:119], v[220:223], v[186:189], v[116:119]
	v_mfma_f32_16x16x32_bf16 v[108:111], v[228:231], v[186:189], v[108:111]
	v_mfma_f32_16x16x32_bf16 v[100:103], v[220:223], v[194:197], v[100:103]
	v_mfma_f32_16x16x32_bf16 v[92:95], v[228:231], v[194:197], v[92:95]
	v_mfma_f32_16x16x32_bf16 v[84:87], v[220:223], v[204:207], v[84:87]
	v_mfma_f32_16x16x32_bf16 v[76:79], v[228:231], v[204:207], v[76:79]
	v_mfma_f32_16x16x32_bf16 v[68:71], v[220:223], v[212:215], v[68:71]
	v_mfma_f32_16x16x32_bf16 v[64:67], v[228:231], v[212:215], v[64:67]
	v_mfma_f32_16x16x32_bf16 v[116:119], v[224:227], v[190:193], v[116:119]
	v_mfma_f32_16x16x32_bf16 v[108:111], v[232:235], v[190:193], v[108:111]
	v_mfma_f32_16x16x32_bf16 v[100:103], v[224:227], v[198:201], v[100:103]
	v_mfma_f32_16x16x32_bf16 v[92:95], v[232:235], v[198:201], v[92:95]
	v_mfma_f32_16x16x32_bf16 v[84:87], v[224:227], v[208:211], v[84:87]
	v_mfma_f32_16x16x32_bf16 v[76:79], v[232:235], v[208:211], v[76:79]
	v_mfma_f32_16x16x32_bf16 v[68:71], v[224:227], v[216:219], v[68:71]
	v_mfma_f32_16x16x32_bf16 v[64:67], v[232:235], v[216:219], v[64:67]
	s_setprio 0
	s_barrier
	ds_read_b128 v[186:189], v163 offset:49152
	ds_read_b128 v[190:193], v163 offset:50176
	ds_read_b128 v[194:197], v163 offset:51200
	ds_read_b128 v[198:201], v163 offset:52224
	ds_read_b128 v[204:207], v163 offset:53248
	ds_read_b128 v[208:211], v163 offset:54272
	ds_read_b128 v[212:215], v163 offset:55296
	ds_read_b128 v[216:219], v163 offset:56320
	s_mov_b32 m0, s54
	v_lshl_add_u64 v[144:145], v[144:145], 0, s[12:13]
	global_load_lds_dwordx4 v[144:145], off
	v_lshl_add_u64 v[144:145], v[236:237], 0, s[12:13]
	s_mov_b32 m0, s55
	s_nop 0
	global_load_lds_dwordx4 v[144:145], off
	s_mov_b32 m0, s56
	v_lshl_add_u64 v[144:145], v[238:239], 0, s[12:13]
	global_load_lds_dwordx4 v[144:145], off
	v_lshl_add_u64 v[144:145], v[240:241], 0, s[12:13]
	s_mov_b32 m0, s57
	s_nop 0
	global_load_lds_dwordx4 v[144:145], off
	s_add_u32 s34, s34, 0x40080
	s_addc_u32 s35, s35, 0
	s_mov_b32 m0, s58
	v_lshl_add_u64 v[144:145], s[34:35], 0, v[128:129]
	global_load_lds_dwordx4 v[144:145], off
	v_lshl_add_u64 v[144:145], s[34:35], 0, v[130:131]
	s_mov_b32 m0, s59
	s_nop 0
	global_load_lds_dwordx4 v[144:145], off
	s_waitcnt lgkmcnt(0)
	s_waitcnt vmcnt(8)
	s_barrier
	s_setprio 1
	v_mfma_f32_16x16x32_bf16 v[60:63], v[170:173], v[186:189], v[60:63]
	v_mfma_f32_16x16x32_bf16 v[56:59], v[178:181], v[186:189], v[56:59]
	v_mfma_f32_16x16x32_bf16 v[48:51], v[170:173], v[194:197], v[48:51]
	v_mfma_f32_16x16x32_bf16 v[40:43], v[178:181], v[194:197], v[40:43]
	v_mfma_f32_16x16x32_bf16 v[32:35], v[170:173], v[204:207], v[32:35]
	v_mfma_f32_16x16x32_bf16 v[24:27], v[178:181], v[204:207], v[24:27]
	v_mfma_f32_16x16x32_bf16 v[16:19], v[170:173], v[212:215], v[16:19]
	v_mfma_f32_16x16x32_bf16 v[8:11], v[178:181], v[212:215], v[8:11]
	v_mfma_f32_16x16x32_bf16 v[60:63], v[174:177], v[190:193], v[60:63]
	v_mfma_f32_16x16x32_bf16 v[56:59], v[182:185], v[190:193], v[56:59]
	v_mfma_f32_16x16x32_bf16 v[48:51], v[174:177], v[198:201], v[48:51]
	v_mfma_f32_16x16x32_bf16 v[40:43], v[182:185], v[198:201], v[40:43]
	v_mfma_f32_16x16x32_bf16 v[32:35], v[174:177], v[208:211], v[32:35]
	v_mfma_f32_16x16x32_bf16 v[24:27], v[182:185], v[208:211], v[24:27]
	v_mfma_f32_16x16x32_bf16 v[16:19], v[174:177], v[216:219], v[16:19]
	v_mfma_f32_16x16x32_bf16 v[8:11], v[182:185], v[216:219], v[8:11]
	v_mfma_f32_16x16x32_bf16 v[52:55], v[220:223], v[186:189], v[52:55]
	v_mfma_f32_16x16x32_bf16 v[44:47], v[228:231], v[186:189], v[44:47]
	v_mfma_f32_16x16x32_bf16 v[36:39], v[220:223], v[194:197], v[36:39]
	v_mfma_f32_16x16x32_bf16 v[28:31], v[228:231], v[194:197], v[28:31]
	v_mfma_f32_16x16x32_bf16 v[20:23], v[220:223], v[204:207], v[20:23]
	v_mfma_f32_16x16x32_bf16 v[12:15], v[228:231], v[204:207], v[12:15]
	v_mfma_f32_16x16x32_bf16 v[4:7], v[220:223], v[212:215], v[4:7]
	v_mfma_f32_16x16x32_bf16 v[0:3], v[228:231], v[212:215], v[0:3]
	v_mfma_f32_16x16x32_bf16 v[52:55], v[224:227], v[190:193], v[52:55]
	v_mfma_f32_16x16x32_bf16 v[44:47], v[232:235], v[190:193], v[44:47]
	v_mfma_f32_16x16x32_bf16 v[36:39], v[224:227], v[198:201], v[36:39]
	v_mfma_f32_16x16x32_bf16 v[28:31], v[232:235], v[198:201], v[28:31]
	v_mfma_f32_16x16x32_bf16 v[20:23], v[224:227], v[208:211], v[20:23]
	v_mfma_f32_16x16x32_bf16 v[12:15], v[232:235], v[208:211], v[12:15]
	v_mfma_f32_16x16x32_bf16 v[4:7], v[224:227], v[216:219], v[4:7]
	v_mfma_f32_16x16x32_bf16 v[0:3], v[232:235], v[216:219], v[0:3]
	s_setprio 0
	s_add_i32 s41, s41, 2
	s_add_u32 s30, s30, 0x100
	s_addc_u32 s31, s31, 0
	s_add_u32 s39, s39, 0x100
	s_addc_u32 s40, s40, 0
	s_cmp_gt_u32 s41, 13
	s_barrier
	s_cbranch_scc0 .LBB0_1243
	s_and_b64 vcc, exec, s[26:27]
	s_cbranch_vccnz .Lp9_noA
	s_add_u32 s94, s18, 0x40080
	s_addc_u32 s95, s19, 0
	v_lshl_add_u64 v[144:145], s[94:95], 0, v[134:135]
	s_add_i32 m0, s48, 0xc000
	s_nop 0
	global_load_lds_dwordx4 v[144:145], off
	v_lshl_add_u64 v[144:145], s[94:95], 0, v[136:137]
	s_add_i32 m0, s48, 0xe000
	s_nop 0
	global_load_lds_dwordx4 v[144:145], off
.Lp9_noA:
	v_lshlrev_b32_e32 v170, 2, v160
	v_add_u32_e32 v170, s92, v170
	ds_read_b32 v174, v170
	ds_read_b32 v176, v170 offset:64
	ds_read_b32 v156, v170 offset:128
	ds_read_b32 v154, v170 offset:192
	ds_read_b32 v152, v170 offset:512
	ds_read_b32 v150, v170 offset:576
	ds_read_b32 v148, v170 offset:640
	ds_read_b32 v146, v170 offset:704
	v_lshl_add_u32 v144, s42, 8, v160
	v_add_u32_e32 v145, 0x80, v144
	s_cmpk_lt_i32 s42, 0x80
	s_waitcnt lgkmcnt(0)
	v_pk_mul_f32 v[124:125], v[124:125], v[174:175] op_sel_hi:[1,0]
	v_mul_f32_e32 v172, 0xbfb8aa3b, v125
	v_exp_f32_e32 v173, v172
	v_mul_f32_e32 v169, 0xbfb8aa3b, v124
	v_exp_f32_e32 v169, v169
	v_pk_mul_f32 v[126:127], v[126:127], v[174:175] op_sel_hi:[1,0]
	v_pk_mul_f32 v[118:119], v[118:119], v[174:175] op_sel_hi:[1,0]
	v_add_f32_e32 v169, 1.0, v169
	v_rcp_f32_e32 v172, v169
	v_add_f32_e32 v169, 1.0, v173
	v_mul_f32_e32 v173, 0xbfb8aa3b, v126
	v_exp_f32_e32 v175, v173
	v_mul_f32_e32 v173, 0xbfb8aa3b, v127
	v_exp_f32_e32 v177, v173
	v_rcp_f32_e32 v173, v169
	v_add_f32_e32 v169, 1.0, v175
	v_rcp_f32_e32 v178, v169
	v_add_f32_e32 v169, 1.0, v177
	v_rcp_f32_e32 v179, v169
	v_pk_mul_f32 v[116:117], v[116:117], v[174:175] op_sel_hi:[1,0]
	v_pk_mul_f32 v[124:125], v[124:125], v[172:173]
	v_pk_mul_f32 v[120:121], v[120:121], v[174:175] op_sel_hi:[1,0]
	v_pk_mul_f32 v[116:117], v[116:117], v[124:125]
	v_pk_mul_f32 v[124:125], v[126:127], v[178:179]
	v_pk_mul_f32 v[122:123], v[122:123], v[174:175] op_sel_hi:[1,0]
	v_pk_mul_f32 v[118:119], v[118:119], v[124:125]
	v_mul_f32_e32 v124, 0xbfb8aa3b, v120
	v_mul_f32_e32 v125, 0xbfb8aa3b, v121
	v_exp_f32_e32 v124, v124
	v_exp_f32_e32 v125, v125
	v_mul_f32_e32 v126, 0xbfb8aa3b, v122
	v_mul_f32_e32 v127, 0xbfb8aa3b, v123
	v_exp_f32_e32 v126, v126
	v_exp_f32_e32 v127, v127
	v_add_f32_e32 v124, 1.0, v124
	v_add_f32_e32 v125, 1.0, v125
	v_rcp_f32_e32 v124, v124
	v_rcp_f32_e32 v125, v125
	v_add_f32_e32 v126, 1.0, v126
	v_add_f32_e32 v127, 1.0, v127
	v_rcp_f32_e32 v126, v126
	v_rcp_f32_e32 v127, v127
	v_pk_mul_f32 v[108:109], v[108:109], v[174:175] op_sel_hi:[1,0]
	v_pk_mul_f32 v[120:121], v[120:121], v[124:125]
	v_lshl_or_b32 v170, s28, 7, v161
	v_pk_mul_f32 v[110:111], v[110:111], v[174:175] op_sel_hi:[1,0]
	v_pk_mul_f32 v[108:109], v[108:109], v[120:121]
	v_pk_mul_f32 v[120:121], v[122:123], v[126:127]
	v_ashrrev_i32_e32 v171, 31, v170
	v_pk_mul_f32 v[110:111], v[110:111], v[120:121]
	v_cvt_pk_bf16_f32 v116, v116, v117
	v_cvt_pk_bf16_f32 v117, v118, v119
	v_cvt_pk_bf16_f32 v118, v108, v109
	v_mov_b64_e32 v[108:109], s[6:7]
	v_cvt_pk_bf16_f32 v119, v110, v111
	v_mad_i64_i32 v[120:121], s[28:29], v144, s68, v[108:109]
	v_lshlrev_b64 v[110:111], 1, v[170:171]
	v_lshl_add_u64 v[120:121], v[120:121], 0, v[110:111]
	v_pk_mul_f32 v[112:113], v[112:113], v[176:177] op_sel_hi:[1,0]
	global_store_dwordx4 v[120:121], v[116:119], off
	v_pk_mul_f32 v[114:115], v[114:115], v[176:177] op_sel_hi:[1,0]
	v_pk_mul_f32 v[100:101], v[100:101], v[176:177] op_sel_hi:[1,0]
	v_mul_f32_e32 v116, 0xbfb8aa3b, v112
	v_mul_f32_e32 v117, 0xbfb8aa3b, v113
	v_exp_f32_e32 v116, v116
	v_exp_f32_e32 v117, v117
	v_mul_f32_e32 v118, 0xbfb8aa3b, v114
	v_mul_f32_e32 v119, 0xbfb8aa3b, v115
	v_exp_f32_e32 v118, v118
	v_exp_f32_e32 v119, v119
	v_add_f32_e32 v116, 1.0, v116
	v_add_f32_e32 v117, 1.0, v117
	v_rcp_f32_e32 v116, v116
	v_rcp_f32_e32 v117, v117
	v_add_f32_e32 v118, 1.0, v118
	v_add_f32_e32 v119, 1.0, v119
	v_rcp_f32_e32 v118, v118
	v_rcp_f32_e32 v119, v119
	v_pk_mul_f32 v[112:113], v[112:113], v[116:117]
	v_pk_mul_f32 v[102:103], v[102:103], v[176:177] op_sel_hi:[1,0]
	v_pk_mul_f32 v[100:101], v[100:101], v[112:113]
	v_pk_mul_f32 v[112:113], v[114:115], v[118:119]
	v_pk_mul_f32 v[104:105], v[104:105], v[176:177] op_sel_hi:[1,0]
	v_pk_mul_f32 v[102:103], v[102:103], v[112:113]
	v_pk_mul_f32 v[106:107], v[106:107], v[176:177] op_sel_hi:[1,0]
	v_mul_f32_e32 v112, 0xbfb8aa3b, v104
	v_mul_f32_e32 v113, 0xbfb8aa3b, v105
	v_exp_f32_e32 v112, v112
	v_exp_f32_e32 v113, v113
	v_mul_f32_e32 v114, 0xbfb8aa3b, v106
	v_mul_f32_e32 v115, 0xbfb8aa3b, v107
	v_exp_f32_e32 v114, v114
	v_exp_f32_e32 v115, v115
	v_add_f32_e32 v112, 1.0, v112
	v_add_f32_e32 v113, 1.0, v113
	v_rcp_f32_e32 v112, v112
	v_rcp_f32_e32 v113, v113
	v_add_f32_e32 v114, 1.0, v114
	v_add_f32_e32 v115, 1.0, v115
	v_rcp_f32_e32 v114, v114
	v_rcp_f32_e32 v115, v115
	v_pk_mul_f32 v[92:93], v[92:93], v[176:177] op_sel_hi:[1,0]
	v_pk_mul_f32 v[104:105], v[104:105], v[112:113]
	v_pk_mul_f32 v[94:95], v[94:95], v[176:177] op_sel_hi:[1,0]
	v_pk_mul_f32 v[104:105], v[92:93], v[104:105]
	v_pk_mul_f32 v[92:93], v[106:107], v[114:115]
	v_or_b32_e32 v112, 16, v144
	v_pk_mul_f32 v[106:107], v[94:95], v[92:93]
	v_cvt_pk_bf16_f32 v92, v100, v101
	v_mad_i64_i32 v[100:101], s[28:29], v112, s68, v[108:109]
	v_cvt_pk_bf16_f32 v93, v102, v103
	v_cvt_pk_bf16_f32 v94, v104, v105
	v_cvt_pk_bf16_f32 v95, v106, v107
	v_lshl_add_u64 v[100:101], v[100:101], 0, v[110:111]
	global_store_dwordx4 v[100:101], v[92:95], off
	v_pk_mul_f32 v[86:87], v[86:87], v[156:157] op_sel_hi:[1,0]
	v_pk_mul_f32 v[88:89], v[88:89], v[156:157] op_sel_hi:[1,0]
	v_pk_mul_f32 v[92:93], v[98:99], v[156:157] op_sel_hi:[1,0]
	v_pk_mul_f32 v[94:95], v[96:97], v[156:157] op_sel_hi:[1,0]
	v_mul_f32_e32 v98, 0xbfb8aa3b, v92
	v_mul_f32_e32 v99, 0xbfb8aa3b, v93
	v_mul_f32_e32 v96, 0xbfb8aa3b, v94
	v_mul_f32_e32 v97, 0xbfb8aa3b, v95
	v_exp_f32_e32 v98, v98
	v_exp_f32_e32 v99, v99
	v_exp_f32_e32 v96, v96
	v_exp_f32_e32 v97, v97
	v_add_f32_e32 v98, 1.0, v98
	v_add_f32_e32 v99, 1.0, v99
	v_add_f32_e32 v96, 1.0, v96
	v_add_f32_e32 v97, 1.0, v97
	v_rcp_f32_e32 v98, v98
	v_rcp_f32_e32 v99, v99
	v_rcp_f32_e32 v96, v96
	v_rcp_f32_e32 v97, v97
	v_pk_mul_f32 v[84:85], v[84:85], v[156:157] op_sel_hi:[1,0]
	v_pk_mul_f32 v[92:93], v[92:93], v[98:99]
	v_pk_mul_f32 v[90:91], v[90:91], v[156:157] op_sel_hi:[1,0]
	v_pk_mul_f32 v[94:95], v[94:95], v[96:97]
	v_pk_mul_f32 v[86:87], v[86:87], v[92:93]
	v_mul_f32_e32 v92, 0xbfb8aa3b, v88
	v_mul_f32_e32 v93, 0xbfb8aa3b, v89
	v_pk_mul_f32 v[84:85], v[84:85], v[94:95]
	v_exp_f32_e32 v92, v92
	v_exp_f32_e32 v93, v93
	v_mul_f32_e32 v94, 0xbfb8aa3b, v90
	v_mul_f32_e32 v95, 0xbfb8aa3b, v91
	v_exp_f32_e32 v94, v94
	v_exp_f32_e32 v95, v95
	v_add_f32_e32 v92, 1.0, v92
	v_add_f32_e32 v93, 1.0, v93
	v_rcp_f32_e32 v92, v92
	v_rcp_f32_e32 v93, v93
	v_add_f32_e32 v94, 1.0, v94
	v_add_f32_e32 v95, 1.0, v95
	v_rcp_f32_e32 v94, v94
	v_rcp_f32_e32 v95, v95
	v_pk_mul_f32 v[76:77], v[76:77], v[156:157] op_sel_hi:[1,0]
	v_pk_mul_f32 v[88:89], v[88:89], v[92:93]
	v_pk_mul_f32 v[78:79], v[78:79], v[156:157] op_sel_hi:[1,0]
	v_pk_mul_f32 v[88:89], v[76:77], v[88:89]
	v_pk_mul_f32 v[76:77], v[90:91], v[94:95]
	v_or_b32_e32 v92, 32, v144
	v_pk_mul_f32 v[90:91], v[78:79], v[76:77]
	v_cvt_pk_bf16_f32 v76, v84, v85
	v_mad_i64_i32 v[84:85], s[28:29], v92, s68, v[108:109]
	v_cvt_pk_bf16_f32 v77, v86, v87
	v_cvt_pk_bf16_f32 v78, v88, v89
	v_cvt_pk_bf16_f32 v79, v90, v91
	v_lshl_add_u64 v[84:85], v[84:85], 0, v[110:111]
	global_store_dwordx4 v[84:85], v[76:79], off
	v_pk_mul_f32 v[70:71], v[70:71], v[154:155] op_sel_hi:[1,0]
	v_pk_mul_f32 v[72:73], v[72:73], v[154:155] op_sel_hi:[1,0]
	v_pk_mul_f32 v[76:77], v[82:83], v[154:155] op_sel_hi:[1,0]
	v_pk_mul_f32 v[78:79], v[80:81], v[154:155] op_sel_hi:[1,0]
	v_mul_f32_e32 v82, 0xbfb8aa3b, v76
	v_mul_f32_e32 v83, 0xbfb8aa3b, v77
	v_mul_f32_e32 v80, 0xbfb8aa3b, v78
	v_mul_f32_e32 v81, 0xbfb8aa3b, v79
	v_exp_f32_e32 v82, v82
	v_exp_f32_e32 v83, v83
	v_exp_f32_e32 v80, v80
	v_exp_f32_e32 v81, v81
	v_add_f32_e32 v82, 1.0, v82
	v_add_f32_e32 v83, 1.0, v83
	v_add_f32_e32 v80, 1.0, v80
	v_add_f32_e32 v81, 1.0, v81
	v_rcp_f32_e32 v82, v82
	v_rcp_f32_e32 v83, v83
	v_rcp_f32_e32 v80, v80
	v_rcp_f32_e32 v81, v81
	v_pk_mul_f32 v[68:69], v[68:69], v[154:155] op_sel_hi:[1,0]
	v_pk_mul_f32 v[76:77], v[76:77], v[82:83]
	v_pk_mul_f32 v[74:75], v[74:75], v[154:155] op_sel_hi:[1,0]
	v_pk_mul_f32 v[78:79], v[78:79], v[80:81]
	v_pk_mul_f32 v[70:71], v[70:71], v[76:77]
	v_mul_f32_e32 v76, 0xbfb8aa3b, v72
	v_mul_f32_e32 v77, 0xbfb8aa3b, v73
	v_pk_mul_f32 v[68:69], v[68:69], v[78:79]
	v_exp_f32_e32 v76, v76
	v_exp_f32_e32 v77, v77
	v_mul_f32_e32 v78, 0xbfb8aa3b, v74
	v_mul_f32_e32 v79, 0xbfb8aa3b, v75
	v_exp_f32_e32 v78, v78
	v_exp_f32_e32 v79, v79
	v_add_f32_e32 v76, 1.0, v76
	v_add_f32_e32 v77, 1.0, v77
	v_rcp_f32_e32 v76, v76
	v_rcp_f32_e32 v77, v77
	v_add_f32_e32 v78, 1.0, v78
	v_add_f32_e32 v79, 1.0, v79
	v_rcp_f32_e32 v78, v78
	v_rcp_f32_e32 v79, v79
	v_pk_mul_f32 v[64:65], v[64:65], v[154:155] op_sel_hi:[1,0]
	v_pk_mul_f32 v[72:73], v[72:73], v[76:77]
	v_pk_mul_f32 v[66:67], v[66:67], v[154:155] op_sel_hi:[1,0]
	v_pk_mul_f32 v[72:73], v[64:65], v[72:73]
	v_pk_mul_f32 v[64:65], v[74:75], v[78:79]
	v_or_b32_e32 v76, 48, v144
	v_pk_mul_f32 v[74:75], v[66:67], v[64:65]
	v_cvt_pk_bf16_f32 v64, v68, v69
	v_mad_i64_i32 v[68:69], s[28:29], v76, s68, v[108:109]
	v_cvt_pk_bf16_f32 v65, v70, v71
	v_cvt_pk_bf16_f32 v66, v72, v73
	v_cvt_pk_bf16_f32 v67, v74, v75
	v_lshl_add_u64 v[68:69], v[68:69], 0, v[110:111]
	v_pk_mul_f32 v[60:61], v[60:61], v[152:153] op_sel_hi:[1,0]
	global_store_dwordx4 v[68:69], v[64:67], off
	v_pk_mul_f32 v[62:63], v[62:63], v[152:153] op_sel_hi:[1,0]
	v_pk_mul_f32 v[52:53], v[52:53], v[152:153] op_sel_hi:[1,0]
	v_mul_f32_e32 v64, 0xbfb8aa3b, v60
	v_mul_f32_e32 v65, 0xbfb8aa3b, v61
	v_exp_f32_e32 v64, v64
	v_exp_f32_e32 v65, v65
	v_mul_f32_e32 v66, 0xbfb8aa3b, v62
	v_mul_f32_e32 v67, 0xbfb8aa3b, v63
	v_exp_f32_e32 v66, v66
	v_exp_f32_e32 v67, v67
	v_add_f32_e32 v64, 1.0, v64
	v_add_f32_e32 v65, 1.0, v65
	v_rcp_f32_e32 v64, v64
	v_rcp_f32_e32 v65, v65
	v_add_f32_e32 v66, 1.0, v66
	v_add_f32_e32 v67, 1.0, v67
	v_rcp_f32_e32 v66, v66
	v_rcp_f32_e32 v67, v67
	v_pk_mul_f32 v[60:61], v[60:61], v[64:65]
	v_pk_mul_f32 v[54:55], v[54:55], v[152:153] op_sel_hi:[1,0]
	v_pk_mul_f32 v[52:53], v[52:53], v[60:61]
	v_pk_mul_f32 v[60:61], v[62:63], v[66:67]
	v_pk_mul_f32 v[56:57], v[56:57], v[152:153] op_sel_hi:[1,0]
	v_pk_mul_f32 v[54:55], v[54:55], v[60:61]
	v_pk_mul_f32 v[58:59], v[58:59], v[152:153] op_sel_hi:[1,0]
	v_mul_f32_e32 v60, 0xbfb8aa3b, v56
	v_mul_f32_e32 v61, 0xbfb8aa3b, v57
	v_exp_f32_e32 v60, v60
	v_exp_f32_e32 v61, v61
	v_mul_f32_e32 v62, 0xbfb8aa3b, v58
	v_mul_f32_e32 v63, 0xbfb8aa3b, v59
	v_exp_f32_e32 v62, v62
	v_exp_f32_e32 v63, v63
	v_add_f32_e32 v60, 1.0, v60
	v_add_f32_e32 v61, 1.0, v61
	v_rcp_f32_e32 v60, v60
	v_rcp_f32_e32 v61, v61
	v_add_f32_e32 v62, 1.0, v62
	v_add_f32_e32 v63, 1.0, v63
	v_rcp_f32_e32 v62, v62
	v_rcp_f32_e32 v63, v63
	v_pk_mul_f32 v[44:45], v[44:45], v[152:153] op_sel_hi:[1,0]
	v_pk_mul_f32 v[56:57], v[56:57], v[60:61]
	v_pk_mul_f32 v[46:47], v[46:47], v[152:153] op_sel_hi:[1,0]
	v_pk_mul_f32 v[56:57], v[44:45], v[56:57]
	v_pk_mul_f32 v[44:45], v[58:59], v[62:63]
	v_pk_mul_f32 v[38:39], v[38:39], v[150:151] op_sel_hi:[1,0]
	v_pk_mul_f32 v[58:59], v[46:47], v[44:45]
	v_cvt_pk_bf16_f32 v44, v52, v53
	v_mad_i64_i32 v[52:53], s[28:29], v145, s68, v[108:109]
	v_cvt_pk_bf16_f32 v45, v54, v55
	v_cvt_pk_bf16_f32 v46, v56, v57
	v_cvt_pk_bf16_f32 v47, v58, v59
	v_lshl_add_u64 v[52:53], v[52:53], 0, v[110:111]
	global_store_dwordx4 v[52:53], v[44:47], off
	v_pk_mul_f32 v[40:41], v[40:41], v[150:151] op_sel_hi:[1,0]
	v_pk_mul_f32 v[36:37], v[36:37], v[150:151] op_sel_hi:[1,0]
	v_pk_mul_f32 v[44:45], v[50:51], v[150:151] op_sel_hi:[1,0]
	v_pk_mul_f32 v[46:47], v[48:49], v[150:151] op_sel_hi:[1,0]
	v_mul_f32_e32 v50, 0xbfb8aa3b, v44
	v_mul_f32_e32 v51, 0xbfb8aa3b, v45
	v_mul_f32_e32 v48, 0xbfb8aa3b, v46
	v_mul_f32_e32 v49, 0xbfb8aa3b, v47
	v_exp_f32_e32 v50, v50
	v_exp_f32_e32 v51, v51
	v_exp_f32_e32 v48, v48
	v_exp_f32_e32 v49, v49
	v_add_f32_e32 v50, 1.0, v50
	v_add_f32_e32 v51, 1.0, v51
	v_add_f32_e32 v48, 1.0, v48
	v_add_f32_e32 v49, 1.0, v49
	v_rcp_f32_e32 v50, v50
	v_rcp_f32_e32 v51, v51
	v_rcp_f32_e32 v48, v48
	v_rcp_f32_e32 v49, v49
	v_pk_mul_f32 v[42:43], v[42:43], v[150:151] op_sel_hi:[1,0]
	v_pk_mul_f32 v[44:45], v[44:45], v[50:51]
	v_pk_mul_f32 v[46:47], v[46:47], v[48:49]
	v_pk_mul_f32 v[38:39], v[38:39], v[44:45]
	v_mul_f32_e32 v44, 0xbfb8aa3b, v40
	v_mul_f32_e32 v45, 0xbfb8aa3b, v41
	v_pk_mul_f32 v[36:37], v[36:37], v[46:47]
	v_exp_f32_e32 v44, v44
	v_exp_f32_e32 v45, v45
	v_mul_f32_e32 v46, 0xbfb8aa3b, v42
	v_mul_f32_e32 v47, 0xbfb8aa3b, v43
	v_exp_f32_e32 v46, v46
	v_exp_f32_e32 v47, v47
	v_add_f32_e32 v44, 1.0, v44
	v_add_f32_e32 v45, 1.0, v45
	v_rcp_f32_e32 v44, v44
	v_rcp_f32_e32 v45, v45
	v_add_f32_e32 v46, 1.0, v46
	v_add_f32_e32 v47, 1.0, v47
	v_rcp_f32_e32 v46, v46
	v_rcp_f32_e32 v47, v47
	v_pk_mul_f32 v[28:29], v[28:29], v[150:151] op_sel_hi:[1,0]
	v_pk_mul_f32 v[40:41], v[40:41], v[44:45]
	v_pk_mul_f32 v[30:31], v[30:31], v[150:151] op_sel_hi:[1,0]
	v_pk_mul_f32 v[40:41], v[28:29], v[40:41]
	v_pk_mul_f32 v[28:29], v[42:43], v[46:47]
	v_add_u32_e32 v44, 0x90, v144
	v_pk_mul_f32 v[42:43], v[30:31], v[28:29]
	v_cvt_pk_bf16_f32 v28, v36, v37
	v_mad_i64_i32 v[36:37], s[28:29], v44, s68, v[108:109]
	v_cvt_pk_bf16_f32 v29, v38, v39
	v_cvt_pk_bf16_f32 v30, v40, v41
	v_cvt_pk_bf16_f32 v31, v42, v43
	v_lshl_add_u64 v[36:37], v[36:37], 0, v[110:111]
	global_store_dwordx4 v[36:37], v[28:31], off
	v_pk_mul_f32 v[22:23], v[22:23], v[148:149] op_sel_hi:[1,0]
	v_pk_mul_f32 v[24:25], v[24:25], v[148:149] op_sel_hi:[1,0]
	v_pk_mul_f32 v[28:29], v[34:35], v[148:149] op_sel_hi:[1,0]
	v_pk_mul_f32 v[30:31], v[32:33], v[148:149] op_sel_hi:[1,0]
	v_mul_f32_e32 v34, 0xbfb8aa3b, v28
	v_mul_f32_e32 v35, 0xbfb8aa3b, v29
	v_mul_f32_e32 v32, 0xbfb8aa3b, v30
	v_mul_f32_e32 v33, 0xbfb8aa3b, v31
	v_exp_f32_e32 v34, v34
	v_exp_f32_e32 v35, v35
	v_exp_f32_e32 v32, v32
	v_exp_f32_e32 v33, v33
	v_add_f32_e32 v34, 1.0, v34
	v_add_f32_e32 v35, 1.0, v35
	v_add_f32_e32 v32, 1.0, v32
	v_add_f32_e32 v33, 1.0, v33
	v_rcp_f32_e32 v34, v34
	v_rcp_f32_e32 v35, v35
	v_rcp_f32_e32 v32, v32
	v_rcp_f32_e32 v33, v33
	v_pk_mul_f32 v[20:21], v[20:21], v[148:149] op_sel_hi:[1,0]
	v_pk_mul_f32 v[28:29], v[28:29], v[34:35]
	v_pk_mul_f32 v[26:27], v[26:27], v[148:149] op_sel_hi:[1,0]
	v_pk_mul_f32 v[30:31], v[30:31], v[32:33]
	v_pk_mul_f32 v[22:23], v[22:23], v[28:29]
	v_mul_f32_e32 v28, 0xbfb8aa3b, v24
	v_mul_f32_e32 v29, 0xbfb8aa3b, v25
	v_pk_mul_f32 v[20:21], v[20:21], v[30:31]
	v_exp_f32_e32 v28, v28
	v_exp_f32_e32 v29, v29
	v_mul_f32_e32 v30, 0xbfb8aa3b, v26
	v_mul_f32_e32 v31, 0xbfb8aa3b, v27
	v_exp_f32_e32 v30, v30
	v_exp_f32_e32 v31, v31
	v_add_f32_e32 v28, 1.0, v28
	v_add_f32_e32 v29, 1.0, v29
	v_rcp_f32_e32 v28, v28
	v_rcp_f32_e32 v29, v29
	v_add_f32_e32 v30, 1.0, v30
	v_add_f32_e32 v31, 1.0, v31
	v_rcp_f32_e32 v30, v30
	v_rcp_f32_e32 v31, v31
	v_pk_mul_f32 v[12:13], v[12:13], v[148:149] op_sel_hi:[1,0]
	v_pk_mul_f32 v[24:25], v[24:25], v[28:29]
	v_pk_mul_f32 v[14:15], v[14:15], v[148:149] op_sel_hi:[1,0]
	v_pk_mul_f32 v[24:25], v[12:13], v[24:25]
	v_pk_mul_f32 v[12:13], v[26:27], v[30:31]
	v_add_u32_e32 v28, 0xa0, v144
	v_pk_mul_f32 v[26:27], v[14:15], v[12:13]
	v_cvt_pk_bf16_f32 v12, v20, v21
	v_mad_i64_i32 v[20:21], s[28:29], v28, s68, v[108:109]
	v_cvt_pk_bf16_f32 v13, v22, v23
	v_cvt_pk_bf16_f32 v14, v24, v25
	v_cvt_pk_bf16_f32 v15, v26, v27
	v_lshl_add_u64 v[20:21], v[20:21], 0, v[110:111]
	global_store_dwordx4 v[20:21], v[12:15], off
	v_pk_mul_f32 v[6:7], v[6:7], v[146:147] op_sel_hi:[1,0]
	v_pk_mul_f32 v[8:9], v[8:9], v[146:147] op_sel_hi:[1,0]
	v_pk_mul_f32 v[12:13], v[18:19], v[146:147] op_sel_hi:[1,0]
	v_pk_mul_f32 v[14:15], v[16:17], v[146:147] op_sel_hi:[1,0]
	v_mul_f32_e32 v18, 0xbfb8aa3b, v12
	v_mul_f32_e32 v19, 0xbfb8aa3b, v13
	v_mul_f32_e32 v16, 0xbfb8aa3b, v14
	v_mul_f32_e32 v17, 0xbfb8aa3b, v15
	v_exp_f32_e32 v18, v18
	v_exp_f32_e32 v19, v19
	v_exp_f32_e32 v16, v16
	v_exp_f32_e32 v17, v17
	v_add_f32_e32 v18, 1.0, v18
	v_add_f32_e32 v19, 1.0, v19
	v_add_f32_e32 v16, 1.0, v16
	v_add_f32_e32 v17, 1.0, v17
	v_rcp_f32_e32 v18, v18
	v_rcp_f32_e32 v19, v19
	v_rcp_f32_e32 v16, v16
	v_rcp_f32_e32 v17, v17
	v_pk_mul_f32 v[4:5], v[4:5], v[146:147] op_sel_hi:[1,0]
	v_pk_mul_f32 v[12:13], v[12:13], v[18:19]
	v_pk_mul_f32 v[10:11], v[10:11], v[146:147] op_sel_hi:[1,0]
	v_pk_mul_f32 v[14:15], v[14:15], v[16:17]
	v_pk_mul_f32 v[6:7], v[6:7], v[12:13]
	v_mul_f32_e32 v12, 0xbfb8aa3b, v8
	v_mul_f32_e32 v13, 0xbfb8aa3b, v9
	v_pk_mul_f32 v[4:5], v[4:5], v[14:15]
	v_exp_f32_e32 v12, v12
	v_exp_f32_e32 v13, v13
	v_mul_f32_e32 v14, 0xbfb8aa3b, v10
	v_mul_f32_e32 v15, 0xbfb8aa3b, v11
	v_exp_f32_e32 v14, v14
	v_exp_f32_e32 v15, v15
	v_add_f32_e32 v12, 1.0, v12
	v_add_f32_e32 v13, 1.0, v13
	v_rcp_f32_e32 v12, v12
	v_rcp_f32_e32 v13, v13
	v_add_f32_e32 v14, 1.0, v14
	v_add_f32_e32 v15, 1.0, v15
	v_rcp_f32_e32 v14, v14
	v_rcp_f32_e32 v15, v15
	v_pk_mul_f32 v[0:1], v[0:1], v[146:147] op_sel_hi:[1,0]
	v_pk_mul_f32 v[8:9], v[8:9], v[12:13]
	v_pk_mul_f32 v[2:3], v[2:3], v[146:147] op_sel_hi:[1,0]
	v_pk_mul_f32 v[8:9], v[0:1], v[8:9]
	v_pk_mul_f32 v[0:1], v[10:11], v[14:15]
	v_add_u32_e32 v12, 0xb0, v144
	v_pk_mul_f32 v[10:11], v[2:3], v[0:1]
	v_cvt_pk_bf16_f32 v0, v4, v5
	v_mad_i64_i32 v[4:5], s[28:29], v12, s68, v[108:109]
	v_cvt_pk_bf16_f32 v1, v6, v7
	v_cvt_pk_bf16_f32 v2, v8, v9
	v_cvt_pk_bf16_f32 v3, v10, v11
	v_lshl_add_u64 v[4:5], v[4:5], 0, v[110:111]
	global_store_dwordx4 v[4:5], v[0:3], off
	s_cbranch_scc1 .LBB0_1226
	s_waitcnt vmcnt(0)
	buffer_wbl2 sc1
	s_waitcnt vmcnt(0)
	s_waitcnt vmcnt(0)
	s_and_saveexec_b64 s[28:29], s[4:5]
	s_cbranch_execz .LBB0_1225
	s_mov_b64 s[30:31], exec
	v_mbcnt_lo_u32_b32 v0, s30, 0
	v_mbcnt_hi_u32_b32 v0, s31, v0
	v_cmp_eq_u32_e32 vcc, 0, v0
	s_and_b64 s[34:35], exec, vcc
	s_mov_b64 exec, s[34:35]
	s_cbranch_execz .LBB0_1225
	s_bcnt1_i32_b64 s11, s[30:31]
	v_mov_b32_e32 v0, s11
	global_atomic_add v129, v0, s[8:9]
	s_branch .LBB0_1225
